# FFI K-loop: MFMA segments 3+4 and 7+8 back to back (12 barriers per iteration instead of 16), stage-only load segments folded into their predecessors
# baseline (speedup 1.0000x reference)
; #define G_STAGE(bufoff, gbase, o0, h64) do { \
;         __builtin_amdgcn_global_load_lds((const unsigned*)((const char*)(gbase) + (o0)), (LAS unsigned*)(lds + (bufoff) + ldsw), 16, 0, 0); \
;         __builtin_amdgcn_global_load_lds((const unsigned*)((const char*)(gbase) + (h64) + (o0)), (LAS unsigned*)(lds + (bufoff) + ldsw + 8192), 16, 0, 0); } while (0)
; #define G_LDA(dst, b, h) do { _Pragma("unroll") for (int m = 0; m < 4; ++m) _Pragma("unroll") for (int k = 0; k < 2; ++k) dst[m][k] = *(const LAS bf16x8*)(lds + G_SA(b, h) + aoff + m * 2048 + k * 1024); } while (0)
; #define G_LDB(dst, b, h) do { _Pragma("unroll") for (int n = 0; n < 2; ++n) _Pragma("unroll") for (int k = 0; k < 2; ++k) dst[n][k] = *(const LAS bf16x8*)(lds + G_SB(b, h) + boff + n * 2048 + k * 1024); } while (0)
; #define G_WAIT_V(n) asm volatile("s_waitcnt vmcnt(" #n ")" ::: "memory")
; #define G_WAIT_L(n) asm volatile("s_waitcnt lgkmcnt(" #n ")" ::: "memory")
; #define G_BAR __builtin_amdgcn_s_barrier()
; #define G_SCHED __builtin_amdgcn_sched_barrier(0)
;     ...
;         for (int t = 0; t < nt; t += 2) {
;             const bool last = (t == nt - 2);
;             const char* a1 = cA + (size_t)(t + 1) * ckA;
;             const char* a2 = last ? nA : cA + (size_t)(t + 2) * ckA; const char* b2 = last ? nB : cB + (size_t)(t + 2) * kB;
;             const char* a3 = a2 + ckA; const char* b3 = b2 + kB;
;             G_LDB(B0, 0, 0); G_SCHED; G_LDA(At, 0, 0); G_STAGE(G_SA(1, 1), a1 + chA, cA0, qA);
;             G_WAIT_L(8); G_BAR; G_WAIT_L(0); G_MMA(0, 0, At, B0); G_BAR; G_SCHED;
;             G_LDB(B1, 0, 1); G_STAGE(G_SB(0, 0), b2, cB0, qB);
;             G_BAR; G_WAIT_L(0); G_MMA(0, 1, At, B1); G_BAR;
;             G_LDA(At, 0, 1); G_STAGE(G_SA(0, 0), a2, cA0, qA);
;             G_BAR; G_WAIT_L(0); G_MMA(1, 0, At, B0); G_BAR; G_SCHED;
;             G_STAGE(G_SB(0, 1), b2 + chB, cB0, qB);
;             G_WAIT_V(6); G_BAR; G_MMA(1, 1, At, B1); G_BAR;
.Ldbj_FFI_in:
.LBB0_1120:
	s_add_u32 s4, s2, 0xfffc0080
	s_addc_u32 s5, s3, -1
	s_add_i32 s19, 0, 0x10000
	v_add_u32_e32 v0, s19, v149
	ds_read_b128 v[140:143], v0
	ds_read_b128 v[144:147], v0 offset:1024
	ds_read_b128 v[152:155], v0 offset:2048
	ds_read_b128 v[156:159], v0 offset:3072
	s_cmp_eq_u32 s18, 12
	s_cselect_b32 s5, s13, s5
	s_cselect_b32 s4, s12, s4
	s_cselect_b32 s41, s15, s17
	s_cselect_b32 s40, s14, s16
	v_lshl_add_u64 v[184:185], s[2:3], 0, v[138:139]
	s_add_i32 m0, s26, 0xc000
	ds_read_b128 v[160:163], v150
	ds_read_b128 v[164:167], v150 offset:1024
	ds_read_b128 v[172:175], v150 offset:2048
	ds_read_b128 v[176:179], v150 offset:3072
	ds_read_b128 v[180:183], v150 offset:4096
	ds_read_b128 v[196:199], v150 offset:5120
	ds_read_b128 v[200:203], v150 offset:6144
	ds_read_b128 v[204:207], v150 offset:7168
	global_load_lds_dwordx4 v[184:185], off
	v_lshl_add_u64 v[184:185], v[184:185], 0, s[0:1]
	s_add_i32 m0, s26, 0xe000
	s_nop 0
	global_load_lds_dwordx4 v[184:185], off
	s_waitcnt lgkmcnt(8)
	s_barrier
	s_waitcnt lgkmcnt(0)
	v_mfma_f32_16x16x32_bf16 v[132:135], v[140:143], v[160:163], v[132:135]
	v_mfma_f32_16x16x32_bf16 v[124:127], v[152:155], v[160:163], v[124:127]
	v_mfma_f32_16x16x32_bf16 v[116:119], v[140:143], v[172:175], v[116:119]
	v_mfma_f32_16x16x32_bf16 v[108:111], v[152:155], v[172:175], v[108:111]
	v_mfma_f32_16x16x32_bf16 v[100:103], v[140:143], v[180:183], v[100:103]
	v_mfma_f32_16x16x32_bf16 v[92:95], v[152:155], v[180:183], v[92:95]
	v_mfma_f32_16x16x32_bf16 v[84:87], v[140:143], v[200:203], v[84:87]
	v_mfma_f32_16x16x32_bf16 v[76:79], v[152:155], v[200:203], v[76:79]
	v_mfma_f32_16x16x32_bf16 v[132:135], v[144:147], v[164:167], v[132:135]
	v_mfma_f32_16x16x32_bf16 v[124:127], v[156:159], v[164:167], v[124:127]
	v_mfma_f32_16x16x32_bf16 v[116:119], v[144:147], v[176:179], v[116:119]
	v_mfma_f32_16x16x32_bf16 v[108:111], v[156:159], v[176:179], v[108:111]
	v_mfma_f32_16x16x32_bf16 v[100:103], v[144:147], v[196:199], v[100:103]
	v_mfma_f32_16x16x32_bf16 v[92:95], v[156:159], v[196:199], v[92:95]
	v_mfma_f32_16x16x32_bf16 v[84:87], v[144:147], v[204:207], v[84:87]
	v_mfma_f32_16x16x32_bf16 v[76:79], v[156:159], v[204:207], v[76:79]
	s_barrier
	s_add_i32 s39, 0, 0x14000
	s_add_i32 s19, s19, s21
	v_add_u32_e32 v0, s39, v149
	v_lshl_add_u64 v[184:185], s[40:41], 0, v[2:3]
	s_mov_b32 m0, s19
	ds_read_b128 v[208:211], v0
	ds_read_b128 v[212:215], v0 offset:1024
	ds_read_b128 v[216:219], v0 offset:2048
	ds_read_b128 v[220:223], v0 offset:3072
	global_load_lds_dwordx4 v[184:185], off
	v_lshl_add_u64 v[224:225], v[184:185], 0, s[0:1]
	s_add_i32 m0, s19, 0x2000
	s_nop 0
	global_load_lds_dwordx4 v[224:225], off
	s_waitcnt lgkmcnt(0)
	s_barrier
	s_waitcnt lgkmcnt(0)
	v_mfma_f32_16x16x32_bf16 v[128:131], v[208:211], v[160:163], v[128:131]
	v_mfma_f32_16x16x32_bf16 v[120:123], v[216:219], v[160:163], v[120:123]
	v_mfma_f32_16x16x32_bf16 v[112:115], v[208:211], v[172:175], v[112:115]
	v_mfma_f32_16x16x32_bf16 v[104:107], v[216:219], v[172:175], v[104:107]
	v_mfma_f32_16x16x32_bf16 v[96:99], v[208:211], v[180:183], v[96:99]
	v_mfma_f32_16x16x32_bf16 v[88:91], v[216:219], v[180:183], v[88:91]
	v_mfma_f32_16x16x32_bf16 v[80:83], v[208:211], v[200:203], v[80:83]
	v_mfma_f32_16x16x32_bf16 v[72:75], v[216:219], v[200:203], v[72:75]
	v_mfma_f32_16x16x32_bf16 v[128:131], v[212:215], v[164:167], v[128:131]
	v_mfma_f32_16x16x32_bf16 v[120:123], v[220:223], v[164:167], v[120:123]
	v_mfma_f32_16x16x32_bf16 v[112:115], v[212:215], v[176:179], v[112:115]
	v_mfma_f32_16x16x32_bf16 v[104:107], v[220:223], v[176:179], v[104:107]
	v_mfma_f32_16x16x32_bf16 v[96:99], v[212:215], v[196:199], v[96:99]
	v_mfma_f32_16x16x32_bf16 v[88:91], v[220:223], v[196:199], v[88:91]
	v_mfma_f32_16x16x32_bf16 v[80:83], v[212:215], v[204:207], v[80:83]
	v_mfma_f32_16x16x32_bf16 v[72:75], v[220:223], v[204:207], v[72:75]
	s_barrier
	s_mov_b32 m0, s26
	v_lshl_add_u64 v[224:225], s[4:5], 0, v[136:137]
	ds_read_b128 v[160:163], v150 offset:16384
	ds_read_b128 v[164:167], v150 offset:17408
	ds_read_b128 v[172:175], v150 offset:18432
	ds_read_b128 v[176:179], v150 offset:19456
	ds_read_b128 v[180:183], v150 offset:20480
	ds_read_b128 v[196:199], v150 offset:21504
	ds_read_b128 v[200:203], v150 offset:22528
	ds_read_b128 v[204:207], v150 offset:23552
	global_load_lds_dwordx4 v[224:225], off
	v_lshl_add_u64 v[226:227], v[224:225], 0, s[0:1]
	s_mov_b32 m0, s27
	s_nop 0
	global_load_lds_dwordx4 v[226:227], off
	s_add_i32 s4, s39, s21
	v_lshl_add_u64 v[236:237], v[184:185], 0, s[42:43]
	s_mov_b32 m0, s4
	s_nop 0
	global_load_lds_dwordx4 v[236:237], off
	v_lshl_add_u64 v[236:237], v[184:185], 0, s[50:51]
	s_add_i32 m0, s4, 0x2000
	s_nop 0
	global_load_lds_dwordx4 v[236:237], off
	s_waitcnt vmcnt(6)
	s_waitcnt lgkmcnt(0)
	s_barrier
; #define G_STAGE(bufoff, gbase, o0, h64) do { \
;         __builtin_amdgcn_global_load_lds((const unsigned*)((const char*)(gbase) + (o0)), (LAS unsigned*)(lds + (bufoff) + ldsw), 16, 0, 0); \
;         __builtin_amdgcn_global_load_lds((const unsigned*)((const char*)(gbase) + (h64) + (o0)), (LAS unsigned*)(lds + (bufoff) + ldsw + 8192), 16, 0, 0); } while (0)
; #define G_LDA(dst, b, h) do { _Pragma("unroll") for (int m = 0; m < 4; ++m) _Pragma("unroll") for (int k = 0; k < 2; ++k) dst[m][k] = *(const LAS bf16x8*)(lds + G_SA(b, h) + aoff + m * 2048 + k * 1024); } while (0)
; #define G_LDB(dst, b, h) do { _Pragma("unroll") for (int n = 0; n < 2; ++n) _Pragma("unroll") for (int k = 0; k < 2; ++k) dst[n][k] = *(const LAS bf16x8*)(lds + G_SB(b, h) + boff + n * 2048 + k * 1024); } while (0)
; #define G_WAIT_V(n) asm volatile("s_waitcnt vmcnt(" #n ")" ::: "memory")
; #define G_WAIT_L(n) asm volatile("s_waitcnt lgkmcnt(" #n ")" ::: "memory")
; #define G_BAR __builtin_amdgcn_s_barrier()
; #define G_SCHED __builtin_amdgcn_sched_barrier(0)
;     ...
;             G_BAR; G_WAIT_L(0); G_MMA(1, 0, At, B0); G_BAR; G_SCHED;
;             G_STAGE(G_SB(0, 1), b2 + chB, cB0, qB);
;             G_WAIT_V(6); G_BAR; G_MMA(1, 1, At, B1); G_BAR;
;             G_LDB(B0, 1, 0); G_SCHED; G_LDA(At, 1, 0); G_STAGE(G_SA(0, 1), a2 + chA, cA0, qA);
;             G_WAIT_L(8); G_BAR; G_WAIT_L(0); G_MMA(0, 0, At, B0); G_BAR; G_SCHED;
	s_waitcnt lgkmcnt(0)
	v_mfma_f32_16x16x32_bf16 v[68:71], v[140:143], v[160:163], v[68:71]
	v_mfma_f32_16x16x32_bf16 v[60:63], v[152:155], v[160:163], v[60:63]
	v_mfma_f32_16x16x32_bf16 v[52:55], v[140:143], v[172:175], v[52:55]
	v_mfma_f32_16x16x32_bf16 v[44:47], v[152:155], v[172:175], v[44:47]
	v_mfma_f32_16x16x32_bf16 v[36:39], v[140:143], v[180:183], v[36:39]
	v_mfma_f32_16x16x32_bf16 v[28:31], v[152:155], v[180:183], v[28:31]
	v_mfma_f32_16x16x32_bf16 v[20:23], v[140:143], v[200:203], v[20:23]
	v_mfma_f32_16x16x32_bf16 v[12:15], v[152:155], v[200:203], v[12:15]
	v_mfma_f32_16x16x32_bf16 v[68:71], v[144:147], v[164:167], v[68:71]
	v_mfma_f32_16x16x32_bf16 v[60:63], v[156:159], v[164:167], v[60:63]
	v_mfma_f32_16x16x32_bf16 v[52:55], v[144:147], v[176:179], v[52:55]
	v_mfma_f32_16x16x32_bf16 v[44:47], v[156:159], v[176:179], v[44:47]
	v_mfma_f32_16x16x32_bf16 v[36:39], v[144:147], v[196:199], v[36:39]
	v_mfma_f32_16x16x32_bf16 v[28:31], v[156:159], v[196:199], v[28:31]
	v_mfma_f32_16x16x32_bf16 v[20:23], v[144:147], v[204:207], v[20:23]
	v_mfma_f32_16x16x32_bf16 v[12:15], v[156:159], v[204:207], v[12:15]
	v_mfma_f32_16x16x32_bf16 v[64:67], v[208:211], v[160:163], v[64:67]
	v_mfma_f32_16x16x32_bf16 v[56:59], v[216:219], v[160:163], v[56:59]
	v_mfma_f32_16x16x32_bf16 v[48:51], v[208:211], v[172:175], v[48:51]
	v_mfma_f32_16x16x32_bf16 v[40:43], v[216:219], v[172:175], v[40:43]
	v_mfma_f32_16x16x32_bf16 v[32:35], v[208:211], v[180:183], v[32:35]
	v_mfma_f32_16x16x32_bf16 v[24:27], v[216:219], v[180:183], v[24:27]
	v_mfma_f32_16x16x32_bf16 v[16:19], v[208:211], v[200:203], v[16:19]
	v_mfma_f32_16x16x32_bf16 v[8:11], v[216:219], v[200:203], v[8:11]
	v_mfma_f32_16x16x32_bf16 v[64:67], v[212:215], v[164:167], v[64:67]
	v_mfma_f32_16x16x32_bf16 v[56:59], v[220:223], v[164:167], v[56:59]
	v_mfma_f32_16x16x32_bf16 v[48:51], v[212:215], v[176:179], v[48:51]
	v_mfma_f32_16x16x32_bf16 v[40:43], v[220:223], v[176:179], v[40:43]
	v_mfma_f32_16x16x32_bf16 v[32:35], v[212:215], v[196:199], v[32:35]
	v_mfma_f32_16x16x32_bf16 v[24:27], v[220:223], v[196:199], v[24:27]
	v_mfma_f32_16x16x32_bf16 v[16:19], v[212:215], v[204:207], v[16:19]
	v_mfma_f32_16x16x32_bf16 v[8:11], v[220:223], v[204:207], v[8:11]
	s_barrier
	s_add_i32 s4, 0, 0x18000
	v_add_u32_e32 v0, s4, v149
	ds_read_b128 v[140:143], v0
	ds_read_b128 v[144:147], v0 offset:1024
	ds_read_b128 v[152:155], v0 offset:2048
	ds_read_b128 v[156:159], v0 offset:3072
	s_mov_b32 m0, s29
	v_lshl_add_u64 v[208:209], v[224:225], 0, s[42:43]
	ds_read_b128 v[160:163], v150 offset:32768
	ds_read_b128 v[164:167], v150 offset:33792
	ds_read_b128 v[172:175], v150 offset:34816
	ds_read_b128 v[176:179], v150 offset:35840
	ds_read_b128 v[180:183], v150 offset:36864
	ds_read_b128 v[196:199], v150 offset:37888
	ds_read_b128 v[200:203], v150 offset:38912
	ds_read_b128 v[204:207], v150 offset:39936
	global_load_lds_dwordx4 v[208:209], off
	v_lshl_add_u64 v[208:209], v[224:225], 0, s[50:51]
	s_mov_b32 m0, s30
	s_nop 0
	global_load_lds_dwordx4 v[208:209], off
	s_waitcnt lgkmcnt(8)
	s_barrier
	s_waitcnt lgkmcnt(0)
	v_mfma_f32_16x16x32_bf16 v[132:135], v[140:143], v[160:163], v[132:135]
	v_mfma_f32_16x16x32_bf16 v[124:127], v[152:155], v[160:163], v[124:127]
	v_mfma_f32_16x16x32_bf16 v[116:119], v[140:143], v[172:175], v[116:119]
	v_mfma_f32_16x16x32_bf16 v[108:111], v[152:155], v[172:175], v[108:111]
	v_mfma_f32_16x16x32_bf16 v[100:103], v[140:143], v[180:183], v[100:103]
	v_mfma_f32_16x16x32_bf16 v[92:95], v[152:155], v[180:183], v[92:95]
	v_mfma_f32_16x16x32_bf16 v[84:87], v[140:143], v[200:203], v[84:87]
	v_mfma_f32_16x16x32_bf16 v[76:79], v[152:155], v[200:203], v[76:79]
	v_mfma_f32_16x16x32_bf16 v[132:135], v[144:147], v[164:167], v[132:135]
	v_mfma_f32_16x16x32_bf16 v[124:127], v[156:159], v[164:167], v[124:127]
	v_mfma_f32_16x16x32_bf16 v[116:119], v[144:147], v[176:179], v[116:119]
	v_mfma_f32_16x16x32_bf16 v[108:111], v[156:159], v[176:179], v[108:111]
	v_mfma_f32_16x16x32_bf16 v[100:103], v[144:147], v[196:199], v[100:103]
	v_mfma_f32_16x16x32_bf16 v[92:95], v[156:159], v[196:199], v[92:95]
	v_mfma_f32_16x16x32_bf16 v[84:87], v[144:147], v[204:207], v[84:87]
	v_mfma_f32_16x16x32_bf16 v[76:79], v[156:159], v[204:207], v[76:79]
	s_barrier
	s_add_i32 s5, 0, 0x1c000
	s_add_i32 s4, s4, s21
	v_add_u32_e32 v0, s5, v149
	v_lshl_add_u64 v[226:227], v[184:185], 0, s[46:47]
	s_mov_b32 m0, s4
	ds_read_b128 v[208:211], v0
	ds_read_b128 v[212:215], v0 offset:1024
	ds_read_b128 v[216:219], v0 offset:2048
	ds_read_b128 v[220:223], v0 offset:3072
	global_load_lds_dwordx4 v[226:227], off
	v_lshl_add_u64 v[226:227], v[184:185], 0, s[52:53]
	s_add_i32 m0, s4, 0x2000
	s_nop 0
	global_load_lds_dwordx4 v[226:227], off
	s_waitcnt lgkmcnt(0)
	s_barrier
; #define G_STAGE(bufoff, gbase, o0, h64) do { \
;         __builtin_amdgcn_global_load_lds((const unsigned*)((const char*)(gbase) + (o0)), (LAS unsigned*)(lds + (bufoff) + ldsw), 16, 0, 0); \
;         __builtin_amdgcn_global_load_lds((const unsigned*)((const char*)(gbase) + (h64) + (o0)), (LAS unsigned*)(lds + (bufoff) + ldsw + 8192), 16, 0, 0); } while (0)
; #define G_LDA(dst, b, h) do { _Pragma("unroll") for (int m = 0; m < 4; ++m) _Pragma("unroll") for (int k = 0; k < 2; ++k) dst[m][k] = *(const LAS bf16x8*)(lds + G_SA(b, h) + aoff + m * 2048 + k * 1024); } while (0)
; #define G_LDB(dst, b, h) do { _Pragma("unroll") for (int n = 0; n < 2; ++n) _Pragma("unroll") for (int k = 0; k < 2; ++k) dst[n][k] = *(const LAS bf16x8*)(lds + G_SB(b, h) + boff + n * 2048 + k * 1024); } while (0)
; #define G_WAIT_V(n) asm volatile("s_waitcnt vmcnt(" #n ")" ::: "memory")
; #define G_WAIT_L(n) asm volatile("s_waitcnt lgkmcnt(" #n ")" ::: "memory")
; #define G_BAR __builtin_amdgcn_s_barrier()
; #define G_SCHED __builtin_amdgcn_sched_barrier(0)
;     ...
;             G_WAIT_L(8); G_BAR; G_WAIT_L(0); G_MMA(0, 0, At, B0); G_BAR; G_SCHED;
;             G_LDB(B1, 1, 1); G_STAGE(G_SB(1, 0), b3, cB0, qB);
;             G_BAR; G_WAIT_L(0); G_MMA(0, 1, At, B1); G_BAR;
;             G_LDA(At, 1, 1); G_STAGE(G_SA(1, 0), a3, cA0, qA);
;             G_BAR; G_WAIT_L(0); G_MMA(1, 0, At, B0); G_BAR; G_SCHED;
;             G_STAGE(G_SB(1, 1), b3 + chB, cB0, qB);
;             G_WAIT_V(6); G_BAR; G_MMA(1, 1, At, B1); G_BAR;
;         }
	s_waitcnt lgkmcnt(0)
	v_mfma_f32_16x16x32_bf16 v[128:131], v[208:211], v[160:163], v[128:131]
	v_mfma_f32_16x16x32_bf16 v[120:123], v[216:219], v[160:163], v[120:123]
	v_mfma_f32_16x16x32_bf16 v[112:115], v[208:211], v[172:175], v[112:115]
	v_mfma_f32_16x16x32_bf16 v[104:107], v[216:219], v[172:175], v[104:107]
	v_mfma_f32_16x16x32_bf16 v[96:99], v[208:211], v[180:183], v[96:99]
	v_mfma_f32_16x16x32_bf16 v[88:91], v[216:219], v[180:183], v[88:91]
	v_mfma_f32_16x16x32_bf16 v[80:83], v[208:211], v[200:203], v[80:83]
	v_mfma_f32_16x16x32_bf16 v[72:75], v[216:219], v[200:203], v[72:75]
	v_mfma_f32_16x16x32_bf16 v[128:131], v[212:215], v[164:167], v[128:131]
	v_mfma_f32_16x16x32_bf16 v[120:123], v[220:223], v[164:167], v[120:123]
	v_mfma_f32_16x16x32_bf16 v[112:115], v[212:215], v[176:179], v[112:115]
	v_mfma_f32_16x16x32_bf16 v[104:107], v[220:223], v[176:179], v[104:107]
	v_mfma_f32_16x16x32_bf16 v[96:99], v[212:215], v[196:199], v[96:99]
	v_mfma_f32_16x16x32_bf16 v[88:91], v[220:223], v[196:199], v[88:91]
	v_mfma_f32_16x16x32_bf16 v[80:83], v[212:215], v[204:207], v[80:83]
	v_mfma_f32_16x16x32_bf16 v[72:75], v[220:223], v[204:207], v[72:75]
	s_barrier
	s_mov_b32 m0, s31
	v_lshl_add_u64 v[226:227], v[224:225], 0, s[46:47]
	ds_read_b128 v[160:163], v150 offset:49152
	ds_read_b128 v[164:167], v150 offset:50176
	ds_read_b128 v[172:175], v150 offset:51200
	ds_read_b128 v[176:179], v150 offset:52224
	ds_read_b128 v[180:183], v150 offset:53248
	ds_read_b128 v[196:199], v150 offset:54272
	ds_read_b128 v[200:203], v150 offset:55296
	ds_read_b128 v[204:207], v150 offset:56320
	global_load_lds_dwordx4 v[226:227], off
	v_lshl_add_u64 v[224:225], v[224:225], 0, s[52:53]
	s_mov_b32 m0, s34
	s_nop 0
	global_load_lds_dwordx4 v[224:225], off
	s_add_i32 s4, s5, s21
	v_lshl_add_u64 v[238:239], v[184:185], 0, s[54:55]
	s_mov_b32 m0, s4
	s_nop 0
	global_load_lds_dwordx4 v[238:239], off
	v_lshl_add_u64 v[238:239], v[184:185], 0, s[58:59]
	s_add_i32 m0, s4, 0x2000
	s_nop 0
	global_load_lds_dwordx4 v[238:239], off
	s_add_i32 s18, s18, 2
	s_add_u32 s2, s2, 0x100
	s_addc_u32 s3, s3, 0
	s_add_u32 s16, s16, 0x100
	s_addc_u32 s17, s17, 0
	s_cmp_gt_u32 s18, 13
	s_waitcnt vmcnt(6)
	s_waitcnt lgkmcnt(0)
	s_barrier
	s_waitcnt lgkmcnt(0)
	v_mfma_f32_16x16x32_bf16 v[68:71], v[140:143], v[160:163], v[68:71]
	v_mfma_f32_16x16x32_bf16 v[60:63], v[152:155], v[160:163], v[60:63]
	v_mfma_f32_16x16x32_bf16 v[52:55], v[140:143], v[172:175], v[52:55]
	v_mfma_f32_16x16x32_bf16 v[44:47], v[152:155], v[172:175], v[44:47]
	v_mfma_f32_16x16x32_bf16 v[36:39], v[140:143], v[180:183], v[36:39]
	v_mfma_f32_16x16x32_bf16 v[28:31], v[152:155], v[180:183], v[28:31]
	v_mfma_f32_16x16x32_bf16 v[20:23], v[140:143], v[200:203], v[20:23]
	v_mfma_f32_16x16x32_bf16 v[12:15], v[152:155], v[200:203], v[12:15]
	v_mfma_f32_16x16x32_bf16 v[68:71], v[144:147], v[164:167], v[68:71]
	v_mfma_f32_16x16x32_bf16 v[60:63], v[156:159], v[164:167], v[60:63]
	v_mfma_f32_16x16x32_bf16 v[52:55], v[144:147], v[176:179], v[52:55]
	v_mfma_f32_16x16x32_bf16 v[44:47], v[156:159], v[176:179], v[44:47]
	v_mfma_f32_16x16x32_bf16 v[36:39], v[144:147], v[196:199], v[36:39]
	v_mfma_f32_16x16x32_bf16 v[28:31], v[156:159], v[196:199], v[28:31]
	v_mfma_f32_16x16x32_bf16 v[20:23], v[144:147], v[204:207], v[20:23]
	v_mfma_f32_16x16x32_bf16 v[12:15], v[156:159], v[204:207], v[12:15]
	v_mfma_f32_16x16x32_bf16 v[64:67], v[208:211], v[160:163], v[64:67]
	v_mfma_f32_16x16x32_bf16 v[56:59], v[216:219], v[160:163], v[56:59]
	v_mfma_f32_16x16x32_bf16 v[48:51], v[208:211], v[172:175], v[48:51]
	v_mfma_f32_16x16x32_bf16 v[40:43], v[216:219], v[172:175], v[40:43]
	v_mfma_f32_16x16x32_bf16 v[32:35], v[208:211], v[180:183], v[32:35]
	v_mfma_f32_16x16x32_bf16 v[24:27], v[216:219], v[180:183], v[24:27]
	v_mfma_f32_16x16x32_bf16 v[16:19], v[208:211], v[200:203], v[16:19]
	v_mfma_f32_16x16x32_bf16 v[8:11], v[216:219], v[200:203], v[8:11]
	v_mfma_f32_16x16x32_bf16 v[64:67], v[212:215], v[164:167], v[64:67]
	v_mfma_f32_16x16x32_bf16 v[56:59], v[220:223], v[164:167], v[56:59]
	v_mfma_f32_16x16x32_bf16 v[48:51], v[212:215], v[176:179], v[48:51]
	v_mfma_f32_16x16x32_bf16 v[40:43], v[220:223], v[176:179], v[40:43]
	v_mfma_f32_16x16x32_bf16 v[32:35], v[212:215], v[196:199], v[32:35]
	v_mfma_f32_16x16x32_bf16 v[24:27], v[220:223], v[196:199], v[24:27]
	v_mfma_f32_16x16x32_bf16 v[16:19], v[212:215], v[204:207], v[16:19]
	v_mfma_f32_16x16x32_bf16 v[8:11], v[220:223], v[204:207], v[8:11]
	s_cbranch_scc0 .Ldb_FFI_cont
	v_readfirstlane_b32 s101, v186
	s_cmpk_gt_u32 s101, 0xff
	s_cbranch_scc1 .Ldb_FFI_exit
	s_barrier
	s_branch .Ldb_FFI_exit
